# diff attention loop: 11 more softmax exps per two tiles moved into the PV MFMA block; rescale-path scratch quad renamed to free registers; join copies the running max computed in the block
# speedup vs baseline: 1.0096x; 1.0024x over previous
; template <int D0> __device__ __forceinline__ void pv_one(f32x16& od, int vb, bf16x8 pa0, bf16x8 pa1, bf16x8 pa2, bf16x8 pa3) {
;     const s16x4 l0 = tr_read<v_rd_off(D0, 0, 0)>(vb), h0 = tr_read<v_rd_off(D0, 0, 1)>(vb), l1 = tr_read<v_rd_off(D0, 1, 0)>(vb), h1 = tr_read<v_rd_off(D0, 1, 1)>(vb);
;     const s16x4 l2 = tr_read<v_rd_off(D0, 2, 0)>(vb), h2 = tr_read<v_rd_off(D0, 2, 1)>(vb), l3 = tr_read<v_rd_off(D0, 3, 0)>(vb), h3 = tr_read<v_rd_off(D0, 3, 1)>(vb);
;     asm volatile("s_waitcnt lgkmcnt(0)" ::: "memory"); SBAR();
;     ...
;     od = __builtin_amdgcn_mfma_f32_32x32x16_bf16(pa0, PK(l0, h0), od, 0, 0, 0);
;     od = __builtin_amdgcn_mfma_f32_32x32x16_bf16(pa1, PK(l1, h1), od, 0, 0, 0);
;     od = __builtin_amdgcn_mfma_f32_32x32x16_bf16(pa2, PK(l2, h2), od, 0, 0, 0);
;     od = __builtin_amdgcn_mfma_f32_32x32x16_bf16(pa3, PK(l3, h3), od, 0, 0, 0);
;     ...
; }
; __device__ __forceinline__ void pv_d0(f32x16* o, int vb, bf16x8 pa0, bf16x8 pa1, bf16x8 pa2, bf16x8 pa3) {
;     pv_one<0>(o[0], vb, pa0, pa1, pa2, pa3); pv_one<1>(o[1], vb, pa0, pa1, pa2, pa3); pv_one<2>(o[2], vb, pa0, pa1, pa2, pa3); pv_one<3>(o[3], vb, pa0, pa1, pa2, pa3);
; }
; __device__ __forceinline__ void partialSM(f32x16& p0, f32x16& p1, float& m_reg, float& mn, float& alpha, const float C, const float thr) {
;     float pmax = p0[0];
; #pragma unroll
;     for (int r = 1; r < 16; ++r) pmax = fmaxf(pmax, p0[r]);
; #pragma unroll
;     for (int r = 0; r < 16; ++r) pmax = fmaxf(pmax, p1[r]);
;     { auto rr = __builtin_amdgcn_permlane32_swap(__float_as_uint(pmax), __float_as_uint(pmax), false, false);
;       pmax = fmaxf(__uint_as_float(rr[0]), __uint_as_float(rr[1])); }
;     if (__builtin_expect(__all(pmax - m_reg <= thr), 1)) { mn = m_reg; alpha = 1.f; }
;     else { mn = fmaxf(m_reg, pmax); alpha = __builtin_amdgcn_exp2f((m_reg - mn) * C); m_reg = mn; }
;     const float mnC = -mn * C;
; #pragma unroll
;     for (int r = 0; r < 16; ++r) p0[r] = fmaf(p0[r], C, mnC);
; #pragma unroll
;     for (int r = 0; r < 16; ++r) p1[r] = fmaf(p1[r], C, mnC);
; #pragma unroll
;     for (int r = 0; r < 16; ++r) p0[r] = __builtin_amdgcn_exp2f(p0[r]);
; }
; __device__ __forceinline__ void finishSM(f32x16& p0, f32x16& p1, float alpha, float& l_reg, bf16x8& pa0, bf16x8& pa1, bf16x8& pa2, bf16x8& pa3) {
; #pragma unroll
;     for (int r = 0; r < 16; ++r) p1[r] = __builtin_amdgcn_exp2f(p1[r]);
;     float ps = 0;
.LBB0_171:
	s_add_i32 s37, s52, -3
	ds_read_b128 v[64:67], v186 offset:40960
	ds_read_b128 v[68:71], v186 offset:45056
	v_exp_f32_e32 v143, v138
	v_add_f32_e32 v138, 0, v217
	v_add_f32_e32 v138, v219, v138
	s_waitcnt lgkmcnt(1)
	v_mfma_f32_32x32x16_bf16 v[80:95], v[64:67], v[110:113], 0
	v_add_f32_e32 v138, v208, v138
	v_add_f32_e32 v138, v218, v138
	v_add_f32_e32 v138, v153, v138
	ds_read_b128 v[204:207], v188 offset:40960
	ds_read_b128 v[220:223], v188 offset:45056
	v_add_f32_e32 v138, v216, v138
	v_add_f32_e32 v138, v152, v138
	v_add_f32_e32 v138, v202, v138
	s_waitcnt lgkmcnt(2)
	v_mfma_f32_32x32x16_bf16 v[64:79], v[68:71], v[110:113], 0
	v_add_f32_e32 v138, v149, v138
	v_add_f32_e32 v138, v151, v138
	v_add_f32_e32 v138, v147, v138
	v_add_f32_e32 v138, v150, v138
	v_add_f32_e32 v138, v145, v138
	v_exp_f32_e32 v191, v139
	v_add_f32_e32 v138, v148, v138
	s_waitcnt lgkmcnt(1)
	v_mfma_f32_32x32x16_bf16 v[80:95], v[204:207], v[106:109], v[80:95]
	v_exp_f32_e32 v136, v136
	v_add_f32_e32 v138, v144, v138
	v_exp_f32_e32 v137, v137
	v_add_f32_e32 v138, v146, v138
	v_exp_f32_e32 v130, v130
	v_add_f32_e32 v138, v143, v138
	v_exp_f32_e32 v131, v131
	s_waitcnt lgkmcnt(0)
	v_mfma_f32_32x32x16_bf16 v[64:79], v[220:223], v[106:109], v[64:79]
	ds_read_b128 v[204:207], v190 offset:40960
	ds_read_b128 v[220:223], v190 offset:45056
	v_add_f32_e32 v138, v191, v138
	v_exp_f32_e32 v128, v128
	v_add_f32_e32 v138, v136, v138
	v_exp_f32_e32 v129, v129
	v_add_f32_e32 v138, v137, v138
	v_exp_f32_e32 v126, v126
	s_waitcnt lgkmcnt(1)
	v_mfma_f32_32x32x16_bf16 v[80:95], v[204:207], v[102:105], v[80:95]
	v_add_f32_e32 v138, v130, v138
	v_exp_f32_e32 v127, v127
	v_add_f32_e32 v138, v131, v138
	v_exp_f32_e32 v200, v140
	v_add_f32_e32 v138, v128, v138
	v_exp_f32_e32 v210, v141
	v_add_f32_e32 v138, v129, v138
	s_waitcnt lgkmcnt(0)
	v_mfma_f32_32x32x16_bf16 v[64:79], v[220:223], v[102:105], v[64:79]
	ds_read_b128 v[204:207], v192 offset:40960
	ds_read_b128 v[220:223], v192 offset:45056
	v_exp_f32_e32 v134, v134
	v_add_f32_e32 v138, v126, v138
	v_exp_f32_e32 v135, v135
	v_add_f32_e32 v138, v127, v138
	v_exp_f32_e32 v132, v132
	v_add_f32_e32 v138, v200, v138
	s_waitcnt lgkmcnt(1)
	v_mfma_f32_32x32x16_bf16 v[80:95], v[204:207], v[98:101], v[80:95]
	v_exp_f32_e32 v133, v133
	v_add_f32_e32 v138, v210, v138
	v_add_f32_e32 v138, v134, v138
	v_add_f32_e32 v138, v135, v138
	v_add_f32_e32 v138, v132, v138
	v_add_f32_e32 v196, v133, v138
	v_mov_b32_e32 v198, v196
	s_waitcnt lgkmcnt(0)
	v_mfma_f32_32x32x16_bf16 v[64:79], v[220:223], v[98:101], v[64:79]
	v_cvt_pk_bf16_f32 v138, v217, v219
	v_cvt_pk_bf16_f32 v139, v208, v218
	v_cvt_pk_bf16_f32 v140, v153, v216
	v_permlane32_swap_b32_e32 v196, v198
	v_cvt_pk_bf16_f32 v141, v152, v202
	v_permlane32_swap_b32_e32 v138, v140
	v_cvt_pk_bf16_f32 v204, v149, v151
	v_cvt_pk_bf16_f32 v205, v147, v150
	v_cvt_pk_bf16_f32 v206, v145, v148
	v_cvt_pk_bf16_f32 v207, v144, v146
	v_cvt_pk_bf16_f32 v144, v143, v191
	v_cvt_pk_bf16_f32 v145, v136, v137
	v_cvt_pk_bf16_f32 v146, v130, v131
	v_cvt_pk_bf16_f32 v147, v128, v129
	v_cvt_pk_bf16_f32 v148, v126, v127
	v_cvt_pk_bf16_f32 v149, v200, v210
	v_cvt_pk_bf16_f32 v150, v134, v135
	v_cvt_pk_bf16_f32 v151, v132, v133
	v_permlane32_swap_b32_e32 v139, v141
	v_permlane32_swap_b32_e32 v204, v206
	v_permlane32_swap_b32_e32 v205, v207
	v_permlane32_swap_b32_e32 v144, v146
	v_permlane32_swap_b32_e32 v145, v147
	v_permlane32_swap_b32_e32 v148, v150
	v_permlane32_swap_b32_e32 v149, v151
	s_cmp_lt_u32 s37, 30
	s_cselect_b32 s14, 0, 0xffffffe0
	s_cselect_b32 s15, s18, s86
	s_add_i32 s14, s14, s52
	s_lshl_b32 s14, s14, 6
	s_add_i32 s14, s14, s15
	s_sub_i32 s14, s14, 64
	s_ashr_i32 s15, s14, 31
	v_lshl_add_u64 v[126:127], s[14:15], 0, v[164:165]
	v_lshl_add_u64 v[130:131], v[168:169], 0, s[14:15]
	v_mad_u64_u32 v[128:129], s[38:39], v126, s9, v[170:171]
	v_mad_u64_u32 v[132:133], s[38:39], v130, s9, v[170:171]
	v_mad_i32_i24 v129, v127, s9, v129
	v_mad_i32_i24 v133, v131, s9, v133
	v_mad_i64_i32 v[134:135], s[14:15], s14, v195, v[166:167]
	global_load_dwordx4 v[126:129], v[128:129], off
	s_nop 0
	global_load_dwordx4 v[130:133], v[132:133], off
	s_nop 0
	global_load_dwordx4 v[134:137], v[134:135], off
	ds_read_b64_tr_b16 v[216:217], v180 offset:0
	ds_read_b64_tr_b16 v[218:219], v180 offset:0x800
	ds_read_b64_tr_b16 v[220:221], v180 offset:0x1000
	ds_read_b64_tr_b16 v[222:223], v180 offset:0x1800
	ds_read_b64_tr_b16 v[224:225], v180 offset:0x2000
	ds_read_b64_tr_b16 v[226:227], v180 offset:0x2800
	ds_read_b64_tr_b16 v[228:229], v180 offset:0x3000
	ds_read_b64_tr_b16 v[230:231], v180 offset:0x3800
	s_waitcnt lgkmcnt(0)
	s_nop 0
	v_mfma_f32_32x32x16_bf16 v[48:63], v[138:141], v[216:219], v[48:63]
	ds_read_b64_tr_b16 v[216:217], v180 offset:0x200
	ds_read_b64_tr_b16 v[218:219], v180 offset:0xa00
	v_max_f32_e32 v238, v81, v81
	v_max_f32_e32 v239, v80, v80
	v_max_f32_e32 v238, v239, v238
	v_max3_f32 v238, v238, v82, v83
	v_max3_f32 v238, v238, v84, v85
	v_max3_f32 v238, v238, v86, v87
	v_mfma_f32_32x32x16_bf16 v[48:63], v[204:207], v[220:223], v[48:63]
	ds_read_b64_tr_b16 v[220:221], v180 offset:0x1200
	ds_read_b64_tr_b16 v[222:223], v180 offset:0x1a00
	v_max3_f32 v238, v238, v88, v89
	v_max3_f32 v238, v238, v90, v91
	v_max3_f32 v238, v238, v92, v93
	v_max3_f32 v238, v238, v94, v95
	v_max3_f32 v238, v238, v64, v65
	v_max3_f32 v238, v238, v66, v67
	v_mfma_f32_32x32x16_bf16 v[48:63], v[144:147], v[224:227], v[48:63]
	ds_read_b64_tr_b16 v[224:225], v180 offset:0x2200
	ds_read_b64_tr_b16 v[226:227], v180 offset:0x2a00
	v_max3_f32 v238, v238, v68, v69
	v_max3_f32 v238, v238, v70, v71
	v_max3_f32 v238, v238, v72, v73
	v_max3_f32 v238, v238, v74, v75
	v_max3_f32 v238, v238, v76, v77
	v_max3_f32 v238, v238, v78, v79
	v_mfma_f32_32x32x16_bf16 v[48:63], v[148:151], v[228:231], v[48:63]
	ds_read_b64_tr_b16 v[228:229], v180 offset:0x3200
	ds_read_b64_tr_b16 v[230:231], v180 offset:0x3a00
	v_mov_b32_e32 v239, v238
	s_nop 1
	v_permlane32_swap_b32_e32 v238, v239
	v_max_f32_e32 v239, v239, v239
	v_max_f32_e32 v238, v238, v238
	v_max_f32_e32 v238, v238, v239
	s_waitcnt lgkmcnt(0)
; #define SBAR() __builtin_amdgcn_sched_barrier(0)
; template <int OFF> __device__ __forceinline__ s16x4 tr_read(int vb) { s16x4 r; asm volatile("ds_read_b64_tr_b16 %0, %1 offset:%2" : "=&v"(r) : "v"(vb), "i"(OFF) : "memory"); return r; }
; template <int D0> __device__ __forceinline__ void pv_one(f32x16& od, int vb, bf16x8 pa0, bf16x8 pa1, bf16x8 pa2, bf16x8 pa3) {
;     const s16x4 l0 = tr_read<v_rd_off(D0, 0, 0)>(vb), h0 = tr_read<v_rd_off(D0, 0, 1)>(vb), l1 = tr_read<v_rd_off(D0, 1, 0)>(vb), h1 = tr_read<v_rd_off(D0, 1, 1)>(vb);
;     const s16x4 l2 = tr_read<v_rd_off(D0, 2, 0)>(vb), h2 = tr_read<v_rd_off(D0, 2, 1)>(vb), l3 = tr_read<v_rd_off(D0, 3, 0)>(vb), h3 = tr_read<v_rd_off(D0, 3, 1)>(vb);
;     asm volatile("s_waitcnt lgkmcnt(0)" ::: "memory"); SBAR();
;     ...
;     od = __builtin_amdgcn_mfma_f32_32x32x16_bf16(pa0, PK(l0, h0), od, 0, 0, 0);
;     od = __builtin_amdgcn_mfma_f32_32x32x16_bf16(pa1, PK(l1, h1), od, 0, 0, 0);
;     od = __builtin_amdgcn_mfma_f32_32x32x16_bf16(pa2, PK(l2, h2), od, 0, 0, 0);
;     od = __builtin_amdgcn_mfma_f32_32x32x16_bf16(pa3, PK(l3, h3), od, 0, 0, 0);
;     ...
; }
; __device__ __forceinline__ void pv_d0(f32x16* o, int vb, bf16x8 pa0, bf16x8 pa1, bf16x8 pa2, bf16x8 pa3) {
;     pv_one<0>(o[0], vb, pa0, pa1, pa2, pa3); pv_one<1>(o[1], vb, pa0, pa1, pa2, pa3); pv_one<2>(o[2], vb, pa0, pa1, pa2, pa3); pv_one<3>(o[3], vb, pa0, pa1, pa2, pa3);
; }
; __device__ __forceinline__ void partialSM(f32x16& p0, f32x16& p1, float& m_reg, float& mn, float& alpha, const float C, const float thr) {
;     float pmax = p0[0];
; #pragma unroll
;     for (int r = 1; r < 16; ++r) pmax = fmaxf(pmax, p0[r]);
; #pragma unroll
;     for (int r = 0; r < 16; ++r) pmax = fmaxf(pmax, p1[r]);
;     { auto rr = __builtin_amdgcn_permlane32_swap(__float_as_uint(pmax), __float_as_uint(pmax), false, false);
;       pmax = fmaxf(__uint_as_float(rr[0]), __uint_as_float(rr[1])); }
;     if (__builtin_expect(__all(pmax - m_reg <= thr), 1)) { mn = m_reg; alpha = 1.f; }
;     else { mn = fmaxf(m_reg, pmax); alpha = __builtin_amdgcn_exp2f((m_reg - mn) * C); m_reg = mn; }
;     const float mnC = -mn * C;
; #pragma unroll
;     for (int r = 0; r < 16; ++r) p0[r] = fmaf(p0[r], C, mnC);
; #pragma unroll
;     for (int r = 0; r < 16; ++r) p1[r] = fmaf(p1[r], C, mnC);
; #pragma unroll
;     for (int r = 0; r < 16; ++r) p0[r] = __builtin_amdgcn_exp2f(p0[r]);
; }
	v_mfma_f32_32x32x16_bf16 v[32:47], v[138:141], v[216:219], v[32:47]
	ds_read_b64_tr_b16 v[216:217], v180 offset:0x400
	ds_read_b64_tr_b16 v[218:219], v180 offset:0xc00
	v_sub_f32_e32 v239, v238, v142
	v_cmp_ge_f32_e32 vcc, s76, v239
	v_max_f32_e32 v239, v142, v142
	v_max_f32_e32 v238, v239, v238
	v_sub_f32_e32 v239, v142, v238
	v_mul_f32_e32 v239, 0x3e38aa3b, v239
	v_mfma_f32_32x32x16_bf16 v[32:47], v[204:207], v[220:223], v[32:47]
	ds_read_b64_tr_b16 v[220:221], v180 offset:0x1400
	ds_read_b64_tr_b16 v[222:223], v180 offset:0x1c00
	v_exp_f32_e32 v239, v239
	s_cmp_eq_u64 vcc, exec
	s_cselect_b64 s[14:15], -1, 0
	v_cndmask_b32_e64 v200, v239, 1.0, s[14:15]
	v_cmp_gt_f32_e32 vcc, 1.0, v200
	v_mfma_f32_32x32x16_bf16 v[32:47], v[144:147], v[224:227], v[32:47]
	ds_read_b64_tr_b16 v[224:225], v180 offset:0x2400
	ds_read_b64_tr_b16 v[226:227], v180 offset:0x2c00
	v_cndmask_b32_e64 v241, v238, v142, s[14:15]
	v_mul_f32_e32 v239, 0xbe38aa3b, v241
	v_fmamk_f32 v80, v80, 0x3e38aa3b, v239
	v_fmamk_f32 v81, v81, 0x3e38aa3b, v239
	v_mfma_f32_32x32x16_bf16 v[32:47], v[148:151], v[228:231], v[32:47]
	ds_read_b64_tr_b16 v[228:229], v180 offset:0x3400
	ds_read_b64_tr_b16 v[230:231], v180 offset:0x3c00
	v_fmamk_f32 v82, v82, 0x3e38aa3b, v239
	v_fmamk_f32 v83, v83, 0x3e38aa3b, v239
	v_fmamk_f32 v84, v84, 0x3e38aa3b, v239
	v_fmamk_f32 v85, v85, 0x3e38aa3b, v239
	s_waitcnt lgkmcnt(0)
	v_mfma_f32_32x32x16_bf16 v[16:31], v[138:141], v[216:219], v[16:31]
	ds_read_b64_tr_b16 v[216:217], v180 offset:0x600
	ds_read_b64_tr_b16 v[218:219], v180 offset:0xe00
	v_fmamk_f32 v86, v86, 0x3e38aa3b, v239
	v_fmamk_f32 v87, v87, 0x3e38aa3b, v239
	v_fmamk_f32 v88, v88, 0x3e38aa3b, v239
	v_fmamk_f32 v89, v89, 0x3e38aa3b, v239
	v_mfma_f32_32x32x16_bf16 v[16:31], v[204:207], v[220:223], v[16:31]
	ds_read_b64_tr_b16 v[220:221], v180 offset:0x1600
	ds_read_b64_tr_b16 v[222:223], v180 offset:0x1e00
	v_fmamk_f32 v90, v90, 0x3e38aa3b, v239
	v_fmamk_f32 v91, v91, 0x3e38aa3b, v239
	v_fmamk_f32 v92, v92, 0x3e38aa3b, v239
	v_fmamk_f32 v93, v93, 0x3e38aa3b, v239
	v_mfma_f32_32x32x16_bf16 v[16:31], v[144:147], v[224:227], v[16:31]
	ds_read_b64_tr_b16 v[224:225], v180 offset:0x2600
	ds_read_b64_tr_b16 v[226:227], v180 offset:0x2e00
	v_fmamk_f32 v94, v94, 0x3e38aa3b, v239
	v_fmamk_f32 v95, v95, 0x3e38aa3b, v239
	v_mfma_f32_32x32x16_bf16 v[16:31], v[148:151], v[228:231], v[16:31]
	ds_read_b64_tr_b16 v[228:229], v180 offset:0x3600
	ds_read_b64_tr_b16 v[230:231], v180 offset:0x3e00
	v_exp_f32_e32 v153, v81
	v_exp_f32_e32 v152, v83
	v_exp_f32_e32 v142, v88
	v_exp_f32_e32 v143, v90
	s_waitcnt lgkmcnt(0)
	v_mfma_f32_32x32x16_bf16 v[0:15], v[138:141], v[216:219], v[0:15]
	v_mfma_f32_32x32x16_bf16 v[0:15], v[204:207], v[220:223], v[0:15]
	v_exp_f32_e32 v138, v80
	v_mfma_f32_32x32x16_bf16 v[0:15], v[144:147], v[224:227], v[0:15]
	v_exp_f32_e32 v144, v92
	v_exp_f32_e32 v147, v93
	v_exp_f32_e32 v145, v94
	v_exp_f32_e32 v146, v95
	v_exp_f32_e32 v139, v82
	v_mfma_f32_32x32x16_bf16 v[0:15], v[148:151], v[228:231], v[0:15]
	v_exp_f32_e32 v140, v84
	v_exp_f32_e32 v141, v86
	s_barrier
	s_waitcnt vmcnt(5)
	ds_write_b128 v181, v[114:117]
	s_waitcnt vmcnt(4)
	ds_write_b128 v184, v[118:121]
	s_waitcnt vmcnt(3)
	ds_write_b128 v182, v[122:125] offset:32768
	s_cbranch_vccz .LBB0_175
	s_and_saveexec_b64 s[38:39], s[12:13]
	ds_write_b32 v177, v200 offset:49280
	s_or_b64 exec, exec, s[38:39]
	s_waitcnt lgkmcnt(0)
	v_add_u32_e32 v242, v161, v96
	ds_read_b128 v[244:247], v242 offset:49376
	ds_read_b128 v[148:151], v242 offset:49344
	ds_read_b128 v[204:207], v242 offset:49312
	ds_read_b128 v[216:219], v242 offset:49280
	s_waitcnt lgkmcnt(3)
	v_pk_mul_f32 v[60:61], v[60:61], v[244:245]
	s_waitcnt lgkmcnt(2)
	v_pk_mul_f32 v[56:57], v[56:57], v[148:149]
	s_waitcnt lgkmcnt(1)
	v_pk_mul_f32 v[52:53], v[52:53], v[204:205]
	v_pk_mul_f32 v[62:63], v[62:63], v[246:247]
	v_pk_mul_f32 v[58:59], v[58:59], v[150:151]
	v_pk_mul_f32 v[54:55], v[54:55], v[206:207]
	s_waitcnt lgkmcnt(0)
	v_pk_mul_f32 v[50:51], v[50:51], v[218:219]
	v_pk_mul_f32 v[48:49], v[48:49], v[216:217]
	v_pk_mul_f32 v[44:45], v[44:45], v[244:245]
	v_pk_mul_f32 v[40:41], v[40:41], v[148:149]
	v_pk_mul_f32 v[36:37], v[36:37], v[204:205]
	v_pk_mul_f32 v[46:47], v[46:47], v[246:247]
	v_pk_mul_f32 v[42:43], v[42:43], v[150:151]
	v_pk_mul_f32 v[38:39], v[38:39], v[206:207]
	v_pk_mul_f32 v[34:35], v[34:35], v[218:219]
	v_pk_mul_f32 v[32:33], v[32:33], v[216:217]
	v_pk_mul_f32 v[28:29], v[28:29], v[244:245]
	v_pk_mul_f32 v[24:25], v[24:25], v[148:149]
	v_pk_mul_f32 v[20:21], v[20:21], v[204:205]
	v_pk_mul_f32 v[30:31], v[30:31], v[246:247]
	v_pk_mul_f32 v[26:27], v[26:27], v[150:151]
	v_pk_mul_f32 v[22:23], v[22:23], v[206:207]
	v_pk_mul_f32 v[18:19], v[18:19], v[218:219]
	v_pk_mul_f32 v[16:17], v[16:17], v[216:217]
	v_pk_mul_f32 v[12:13], v[12:13], v[244:245]
	v_pk_mul_f32 v[8:9], v[8:9], v[148:149]
	v_pk_mul_f32 v[4:5], v[4:5], v[204:205]
	v_pk_mul_f32 v[14:15], v[14:15], v[246:247]
	v_pk_mul_f32 v[10:11], v[10:11], v[150:151]
	v_pk_mul_f32 v[6:7], v[6:7], v[206:207]
	v_pk_mul_f32 v[2:3], v[2:3], v[218:219]
	v_pk_mul_f32 v[0:1], v[0:1], v[216:217]
; __device__ __forceinline__ void partialSM(f32x16& p0, f32x16& p1, float& m_reg, float& mn, float& alpha, const float C, const float thr) {
;     ...
;     const float mnC = -mn * C;
; #pragma unroll
;     for (int r = 0; r < 16; ++r) p0[r] = fmaf(p0[r], C, mnC);
; #pragma unroll
;     for (int r = 0; r < 16; ++r) p1[r] = fmaf(p1[r], C, mnC);
; #pragma unroll
;     for (int r = 0; r < 16; ++r) p0[r] = __builtin_amdgcn_exp2f(p0[r]);
; }
; __device__ __forceinline__ void finishSM(f32x16& p0, f32x16& p1, float alpha, float& l_reg, bf16x8& pa0, bf16x8& pa1, bf16x8& pa2, bf16x8& pa3) {
; #pragma unroll
;     for (int r = 0; r < 16; ++r) p1[r] = __builtin_amdgcn_exp2f(p1[r]);
;     float ps = 0;
; #pragma unroll
;     for (int r = 0; r < 16; ++r) ps += p0[r];
; #pragma unroll
;     for (int r = 0; r < 16; ++r) ps += p1[r];
;     { auto rr = __builtin_amdgcn_permlane32_swap(__float_as_uint(ps), __float_as_uint(ps), false, false);
;       ps = __uint_as_float(rr[0]) + __uint_as_float(rr[1]); }
;     l_reg = l_reg * alpha + ps;
;     ...
;     PK4(p0, 0, pa0); PK4(p0, 8, pa1); PK4(p1, 0, pa2); PK4(p1, 8, pa3);
.LBB0_175:
	v_mov_b32_e32 v202, v241
	v_mul_f32_e32 v204, 0xbe38aa3b, v202
	v_exp_f32_e32 v151, v85
	v_exp_f32_e32 v150, v87
	v_exp_f32_e32 v149, v89
	v_exp_f32_e32 v148, v91
	v_fmamk_f32 v222, v64, 0x3e38aa3b, v204
	v_fmamk_f32 v223, v65, 0x3e38aa3b, v204
	v_fmamk_f32 v224, v66, 0x3e38aa3b, v204
	v_fmamk_f32 v225, v67, 0x3e38aa3b, v204
	v_fmamk_f32 v226, v68, 0x3e38aa3b, v204
	v_fmamk_f32 v208, v69, 0x3e38aa3b, v204
	v_fmamk_f32 v216, v70, 0x3e38aa3b, v204
	v_fmamk_f32 v217, v71, 0x3e38aa3b, v204
	v_fmamk_f32 v218, v72, 0x3e38aa3b, v204
	v_fmamk_f32 v219, v73, 0x3e38aa3b, v204
	v_fmamk_f32 v220, v74, 0x3e38aa3b, v204
	v_fmamk_f32 v221, v75, 0x3e38aa3b, v204
	v_fmamk_f32 v206, v76, 0x3e38aa3b, v204
	v_fmamk_f32 v227, v77, 0x3e38aa3b, v204
	v_fmamk_f32 v228, v78, 0x3e38aa3b, v204
	v_fmac_f32_e32 v204, 0x3e38aa3b, v79
	s_waitcnt lgkmcnt(0)
	s_barrier
	ds_read_b128 v[64:67], v186 offset:32768
	ds_read_b128 v[68:71], v186 offset:36864
	v_exp_f32_e32 v205, v223
	v_exp_f32_e32 v223, v204
	v_add_f32_e32 v204, 0, v138
	v_add_f32_e32 v204, v153, v204
	s_waitcnt lgkmcnt(1)
	v_mfma_f32_32x32x16_bf16 v[80:95], v[64:67], v[110:113], 0
	v_add_f32_e32 v204, v139, v204
	v_add_f32_e32 v204, v152, v204
	v_add_f32_e32 v204, v140, v204
	ds_read_b128 v[230:233], v188 offset:32768
	ds_read_b128 v[234:237], v188 offset:36864
	v_add_f32_e32 v204, v151, v204
	v_add_f32_e32 v204, v141, v204
	v_add_f32_e32 v204, v150, v204
	s_waitcnt lgkmcnt(2)
	v_mfma_f32_32x32x16_bf16 v[64:79], v[68:71], v[110:113], 0
	v_add_f32_e32 v204, v142, v204
	v_add_f32_e32 v204, v149, v204
	v_add_f32_e32 v204, v143, v204
	v_add_f32_e32 v204, v148, v204
	v_exp_f32_e32 v191, v222
	v_add_f32_e32 v204, v144, v204
	v_add_f32_e32 v204, v147, v204
	s_waitcnt lgkmcnt(1)
	v_mfma_f32_32x32x16_bf16 v[80:95], v[230:233], v[106:109], v[80:95]
	v_exp_f32_e32 v207, v224
	v_add_f32_e32 v204, v145, v204
	v_exp_f32_e32 v210, v225
	v_add_f32_e32 v204, v146, v204
	v_exp_f32_e32 v211, v226
	v_add_f32_e32 v204, v191, v204
	v_exp_f32_e32 v208, v208
	s_waitcnt lgkmcnt(0)
	v_mfma_f32_32x32x16_bf16 v[64:79], v[234:237], v[106:109], v[64:79]
	ds_read_b128 v[230:233], v190 offset:32768
	ds_read_b128 v[234:237], v190 offset:36864
	v_add_f32_e32 v204, v205, v204
	v_exp_f32_e32 v212, v216
	v_add_f32_e32 v204, v207, v204
	v_exp_f32_e32 v213, v217
	v_add_f32_e32 v204, v210, v204
	v_exp_f32_e32 v216, v218
	s_waitcnt lgkmcnt(1)
	v_mfma_f32_32x32x16_bf16 v[80:95], v[230:233], v[102:105], v[80:95]
	v_add_f32_e32 v204, v211, v204
	v_exp_f32_e32 v217, v219
	v_add_f32_e32 v204, v208, v204
	v_exp_f32_e32 v218, v220
	v_add_f32_e32 v204, v212, v204
	v_exp_f32_e32 v219, v221
	v_add_f32_e32 v204, v213, v204
	s_waitcnt lgkmcnt(0)
	v_mfma_f32_32x32x16_bf16 v[64:79], v[234:237], v[102:105], v[64:79]
	ds_read_b128 v[230:233], v192 offset:32768
	ds_read_b128 v[234:237], v192 offset:36864
	v_exp_f32_e32 v220, v206
	v_add_f32_e32 v204, v216, v204
	v_exp_f32_e32 v221, v227
	v_add_f32_e32 v204, v217, v204
	v_exp_f32_e32 v222, v228
	v_add_f32_e32 v204, v218, v204
	s_waitcnt lgkmcnt(1)
	v_mfma_f32_32x32x16_bf16 v[80:95], v[230:233], v[98:101], v[80:95]
	v_add_f32_e32 v204, v219, v204
	v_add_f32_e32 v204, v220, v204
	v_add_f32_e32 v204, v221, v204
	v_add_f32_e32 v204, v222, v204
	v_add_f32_e32 v204, v223, v204
	v_mov_b32_e32 v206, v204
	v_cvt_pk_bf16_f32 v138, v138, v153
	s_waitcnt lgkmcnt(0)
	v_mfma_f32_32x32x16_bf16 v[64:79], v[234:237], v[98:101], v[64:79]
	v_cvt_pk_bf16_f32 v139, v139, v152
	v_cvt_pk_bf16_f32 v140, v140, v151
	v_cvt_pk_bf16_f32 v141, v141, v150
	v_cvt_pk_bf16_f32 v142, v142, v149
	v_cvt_pk_bf16_f32 v143, v143, v148
	v_cvt_pk_bf16_f32 v144, v144, v147
	v_cvt_pk_bf16_f32 v145, v145, v146
	v_cvt_pk_bf16_f32 v146, v191, v205
	v_cvt_pk_bf16_f32 v147, v207, v210
	v_cvt_pk_bf16_f32 v148, v211, v208
	v_cvt_pk_bf16_f32 v149, v212, v213
	v_cvt_pk_bf16_f32 v150, v216, v217
	v_cvt_pk_bf16_f32 v151, v218, v219
	v_cvt_pk_bf16_f32 v152, v220, v221
	v_cvt_pk_bf16_f32 v153, v222, v223
	v_permlane32_swap_b32_e32 v204, v206
	v_permlane32_swap_b32_e32 v138, v140
	v_permlane32_swap_b32_e32 v139, v141
	v_permlane32_swap_b32_e32 v142, v144
	v_permlane32_swap_b32_e32 v143, v145
	v_permlane32_swap_b32_e32 v146, v148
	v_permlane32_swap_b32_e32 v147, v149
	v_permlane32_swap_b32_e32 v150, v152
	v_permlane32_swap_b32_e32 v151, v153
	s_cmp_gt_u32 s37, 32
	s_cbranch_scc1 .LBB0_177
	s_cmp_lt_u32 s37, 29
	s_cselect_b32 s14, 0, 0xffffffe0
	s_cselect_b32 s15, s18, s86
	s_add_i32 s14, s14, s52
	s_lshl_b32 s14, s14, 6
	s_add_i32 s14, s14, s15
	s_ashr_i32 s15, s14, 31
	v_lshl_add_u64 v[114:115], s[14:15], 0, v[164:165]
	v_lshl_add_u64 v[118:119], v[168:169], 0, s[14:15]
	v_mad_u64_u32 v[116:117], s[38:39], v114, s9, v[170:171]
	v_mad_u64_u32 v[120:121], s[38:39], v118, s9, v[170:171]
	v_mad_i32_i24 v117, v115, s9, v117
	v_mad_i32_i24 v121, v119, s9, v121
	v_mad_i64_i32 v[122:123], s[14:15], s14, v195, v[166:167]
	global_load_dwordx4 v[114:117], v[116:117], off
	s_nop 0
	global_load_dwordx4 v[118:121], v[120:121], off
	s_nop 0
	global_load_dwordx4 v[122:125], v[122:123], off
; #define SBAR() __builtin_amdgcn_sched_barrier(0)
; template <int OFF> __device__ __forceinline__ s16x4 tr_read(int vb) { s16x4 r; asm volatile("ds_read_b64_tr_b16 %0, %1 offset:%2" : "=&v"(r) : "v"(vb), "i"(OFF) : "memory"); return r; }
; template <int D0> __device__ __forceinline__ void pv_one(f32x16& od, int vb, bf16x8 pa0, bf16x8 pa1, bf16x8 pa2, bf16x8 pa3) {
;     const s16x4 l0 = tr_read<v_rd_off(D0, 0, 0)>(vb), h0 = tr_read<v_rd_off(D0, 0, 1)>(vb), l1 = tr_read<v_rd_off(D0, 1, 0)>(vb), h1 = tr_read<v_rd_off(D0, 1, 1)>(vb);
;     const s16x4 l2 = tr_read<v_rd_off(D0, 2, 0)>(vb), h2 = tr_read<v_rd_off(D0, 2, 1)>(vb), l3 = tr_read<v_rd_off(D0, 3, 0)>(vb), h3 = tr_read<v_rd_off(D0, 3, 1)>(vb);
;     asm volatile("s_waitcnt lgkmcnt(0)" ::: "memory"); SBAR();
;     ...
;     od = __builtin_amdgcn_mfma_f32_32x32x16_bf16(pa0, PK(l0, h0), od, 0, 0, 0);
;     od = __builtin_amdgcn_mfma_f32_32x32x16_bf16(pa1, PK(l1, h1), od, 0, 0, 0);
;     od = __builtin_amdgcn_mfma_f32_32x32x16_bf16(pa2, PK(l2, h2), od, 0, 0, 0);
;     od = __builtin_amdgcn_mfma_f32_32x32x16_bf16(pa3, PK(l3, h3), od, 0, 0, 0);
;     ...
; }
; __device__ __forceinline__ void pv_d0(f32x16* o, int vb, bf16x8 pa0, bf16x8 pa1, bf16x8 pa2, bf16x8 pa3) {
;     pv_one<0>(o[0], vb, pa0, pa1, pa2, pa3); pv_one<1>(o[1], vb, pa0, pa1, pa2, pa3); pv_one<2>(o[2], vb, pa0, pa1, pa2, pa3); pv_one<3>(o[3], vb, pa0, pa1, pa2, pa3);
; }
; __device__ __forceinline__ void partialSM(f32x16& p0, f32x16& p1, float& m_reg, float& mn, float& alpha, const float C, const float thr) {
;     float pmax = p0[0];
; #pragma unroll
;     for (int r = 1; r < 16; ++r) pmax = fmaxf(pmax, p0[r]);
; #pragma unroll
;     for (int r = 0; r < 16; ++r) pmax = fmaxf(pmax, p1[r]);
;     { auto rr = __builtin_amdgcn_permlane32_swap(__float_as_uint(pmax), __float_as_uint(pmax), false, false);
;       pmax = fmaxf(__uint_as_float(rr[0]), __uint_as_float(rr[1])); }
;     if (__builtin_expect(__all(pmax - m_reg <= thr), 1)) { mn = m_reg; alpha = 1.f; }
;     else { mn = fmaxf(m_reg, pmax); alpha = __builtin_amdgcn_exp2f((m_reg - mn) * C); m_reg = mn; }
;     const float mnC = -mn * C;
; #pragma unroll
;     for (int r = 0; r < 16; ++r) p0[r] = fmaf(p0[r], C, mnC);
; #pragma unroll
;     for (int r = 0; r < 16; ++r) p1[r] = fmaf(p1[r], C, mnC);
; #pragma unroll
;     for (int r = 0; r < 16; ++r) p0[r] = __builtin_amdgcn_exp2f(p0[r]);
; }
.LBB0_177:
	ds_read_b64_tr_b16 v[216:217], v179 offset:0
	ds_read_b64_tr_b16 v[218:219], v179 offset:0x800
	ds_read_b64_tr_b16 v[220:221], v179 offset:0x1000
	ds_read_b64_tr_b16 v[222:223], v179 offset:0x1800
	ds_read_b64_tr_b16 v[224:225], v179 offset:0x2000
	ds_read_b64_tr_b16 v[226:227], v179 offset:0x2800
	ds_read_b64_tr_b16 v[228:229], v179 offset:0x3000
	ds_read_b64_tr_b16 v[230:231], v179 offset:0x3800
	s_waitcnt lgkmcnt(0)
	s_nop 0
	v_mfma_f32_32x32x16_bf16 v[48:63], v[138:141], v[216:219], v[48:63]
	ds_read_b64_tr_b16 v[216:217], v179 offset:0x200
	ds_read_b64_tr_b16 v[218:219], v179 offset:0xa00
	v_max_f32_e32 v238, v81, v81
	v_max_f32_e32 v239, v80, v80
	v_max_f32_e32 v238, v239, v238
	v_max3_f32 v238, v238, v82, v83
	v_max3_f32 v238, v238, v84, v85
	v_max3_f32 v238, v238, v86, v87
	v_mfma_f32_32x32x16_bf16 v[48:63], v[142:145], v[220:223], v[48:63]
	ds_read_b64_tr_b16 v[220:221], v179 offset:0x1200
	ds_read_b64_tr_b16 v[222:223], v179 offset:0x1a00
	v_max3_f32 v238, v238, v88, v89
	v_max3_f32 v238, v238, v90, v91
	v_max3_f32 v238, v238, v92, v93
	v_max3_f32 v238, v238, v94, v95
	v_max3_f32 v238, v238, v64, v65
	v_max3_f32 v238, v238, v66, v67
	v_mfma_f32_32x32x16_bf16 v[48:63], v[146:149], v[224:227], v[48:63]
	ds_read_b64_tr_b16 v[224:225], v179 offset:0x2200
	ds_read_b64_tr_b16 v[226:227], v179 offset:0x2a00
	v_max3_f32 v238, v238, v68, v69
	v_max3_f32 v238, v238, v70, v71
	v_max3_f32 v238, v238, v72, v73
	v_max3_f32 v238, v238, v74, v75
	v_max3_f32 v238, v238, v76, v77
	v_max3_f32 v238, v238, v78, v79
	v_mfma_f32_32x32x16_bf16 v[48:63], v[150:153], v[228:231], v[48:63]
	ds_read_b64_tr_b16 v[228:229], v179 offset:0x3200
	ds_read_b64_tr_b16 v[230:231], v179 offset:0x3a00
	v_mov_b32_e32 v239, v238
	s_nop 1
	v_permlane32_swap_b32_e32 v238, v239
	v_max_f32_e32 v239, v239, v239
	v_max_f32_e32 v238, v238, v238
	v_max_f32_e32 v238, v238, v239
	s_waitcnt lgkmcnt(0)
	v_mfma_f32_32x32x16_bf16 v[32:47], v[138:141], v[216:219], v[32:47]
	ds_read_b64_tr_b16 v[216:217], v179 offset:0x400
	ds_read_b64_tr_b16 v[218:219], v179 offset:0xc00
	v_sub_f32_e32 v239, v238, v202
	v_cmp_ge_f32_e32 vcc, s76, v239
	v_max_f32_e32 v239, v202, v202
	v_max_f32_e32 v238, v239, v238
	v_sub_f32_e32 v239, v202, v238
	v_mul_f32_e32 v239, 0x3e38aa3b, v239
	v_mfma_f32_32x32x16_bf16 v[32:47], v[142:145], v[220:223], v[32:47]
	ds_read_b64_tr_b16 v[220:221], v179 offset:0x1400
	ds_read_b64_tr_b16 v[222:223], v179 offset:0x1c00
	v_exp_f32_e32 v239, v239
	s_cmp_eq_u64 vcc, exec
	s_cselect_b64 s[14:15], -1, 0
	v_cndmask_b32_e64 v240, v239, 1.0, s[14:15]
	v_cmp_gt_f32_e32 vcc, 1.0, v240
	v_mfma_f32_32x32x16_bf16 v[32:47], v[146:149], v[224:227], v[32:47]
	ds_read_b64_tr_b16 v[224:225], v179 offset:0x2400
	ds_read_b64_tr_b16 v[226:227], v179 offset:0x2c00
	v_cndmask_b32_e64 v241, v238, v202, s[14:15]
	v_mul_f32_e32 v239, 0xbe38aa3b, v241
	v_fmamk_f32 v80, v80, 0x3e38aa3b, v239
	v_fmamk_f32 v81, v81, 0x3e38aa3b, v239
	v_mfma_f32_32x32x16_bf16 v[32:47], v[150:153], v[228:231], v[32:47]
	ds_read_b64_tr_b16 v[228:229], v179 offset:0x3400
	ds_read_b64_tr_b16 v[230:231], v179 offset:0x3c00
	v_fmamk_f32 v82, v82, 0x3e38aa3b, v239
	v_fmamk_f32 v83, v83, 0x3e38aa3b, v239
	v_fmamk_f32 v84, v84, 0x3e38aa3b, v239
	v_fmamk_f32 v85, v85, 0x3e38aa3b, v239
	s_waitcnt lgkmcnt(0)
	v_mfma_f32_32x32x16_bf16 v[16:31], v[138:141], v[216:219], v[16:31]
	ds_read_b64_tr_b16 v[216:217], v179 offset:0x600
	ds_read_b64_tr_b16 v[218:219], v179 offset:0xe00
	v_fmamk_f32 v86, v86, 0x3e38aa3b, v239
	v_fmamk_f32 v87, v87, 0x3e38aa3b, v239
	v_fmamk_f32 v88, v88, 0x3e38aa3b, v239
	v_fmamk_f32 v89, v89, 0x3e38aa3b, v239
	v_mfma_f32_32x32x16_bf16 v[16:31], v[142:145], v[220:223], v[16:31]
	ds_read_b64_tr_b16 v[220:221], v179 offset:0x1600
	ds_read_b64_tr_b16 v[222:223], v179 offset:0x1e00
	v_fmamk_f32 v90, v90, 0x3e38aa3b, v239
	v_fmamk_f32 v91, v91, 0x3e38aa3b, v239
	v_fmamk_f32 v92, v92, 0x3e38aa3b, v239
	v_fmamk_f32 v93, v93, 0x3e38aa3b, v239
	v_mfma_f32_32x32x16_bf16 v[16:31], v[146:149], v[224:227], v[16:31]
	ds_read_b64_tr_b16 v[224:225], v179 offset:0x2600
	ds_read_b64_tr_b16 v[226:227], v179 offset:0x2e00
	v_fmamk_f32 v94, v94, 0x3e38aa3b, v239
	v_mfma_f32_32x32x16_bf16 v[16:31], v[150:153], v[228:231], v[16:31]
	ds_read_b64_tr_b16 v[228:229], v179 offset:0x3600
	ds_read_b64_tr_b16 v[230:231], v179 offset:0x3e00
	v_exp_f32_e32 v208, v82
	v_exp_f32_e32 v202, v87
	s_waitcnt lgkmcnt(0)
	v_mfma_f32_32x32x16_bf16 v[0:15], v[138:141], v[216:219], v[0:15]
	v_mfma_f32_32x32x16_bf16 v[0:15], v[142:145], v[220:223], v[0:15]
	v_exp_f32_e32 v145, v92
	v_exp_f32_e32 v144, v94
	v_exp_f32_e32 v217, v80
	v_mfma_f32_32x32x16_bf16 v[0:15], v[146:149], v[224:227], v[0:15]
	v_exp_f32_e32 v149, v88
	v_exp_f32_e32 v147, v90
	v_exp_f32_e32 v148, v93
	v_exp_f32_e32 v219, v81
	v_mfma_f32_32x32x16_bf16 v[0:15], v[150:153], v[228:231], v[0:15]
	v_exp_f32_e32 v218, v83
	v_exp_f32_e32 v216, v85
	v_mov_b32_e32 v143, v240
	s_barrier
	s_waitcnt vmcnt(2)
	ds_write_b128 v181, v[126:129] offset:16384
	s_waitcnt vmcnt(1)
	ds_write_b128 v184, v[130:133] offset:16384
	s_waitcnt vmcnt(0)
	ds_write_b128 v182, v[134:137] offset:40960
	s_cbranch_vccz .LBB0_181
	s_and_saveexec_b64 s[38:39], s[12:13]
	ds_write_b32 v177, v143 offset:49280
	s_or_b64 exec, exec, s[38:39]
	s_waitcnt lgkmcnt(0)
	v_add_u32_e32 v139, v161, v96
	ds_read_b128 v[126:129], v139 offset:49376
	ds_read_b128 v[130:133], v139 offset:49344
	ds_read_b128 v[134:137], v139 offset:49312
	ds_read_b128 v[244:247], v139 offset:49280
	s_waitcnt lgkmcnt(3)
	v_pk_mul_f32 v[60:61], v[60:61], v[126:127]
	s_waitcnt lgkmcnt(2)
	v_pk_mul_f32 v[56:57], v[56:57], v[130:131]
	s_waitcnt lgkmcnt(1)
	v_pk_mul_f32 v[52:53], v[52:53], v[134:135]
	v_pk_mul_f32 v[62:63], v[62:63], v[128:129]
	v_pk_mul_f32 v[58:59], v[58:59], v[132:133]
	v_pk_mul_f32 v[54:55], v[54:55], v[136:137]
	s_waitcnt lgkmcnt(0)
	v_pk_mul_f32 v[50:51], v[50:51], v[246:247]
	v_pk_mul_f32 v[48:49], v[48:49], v[244:245]
	v_pk_mul_f32 v[44:45], v[44:45], v[126:127]
	v_pk_mul_f32 v[40:41], v[40:41], v[130:131]
	v_pk_mul_f32 v[36:37], v[36:37], v[134:135]
	v_pk_mul_f32 v[46:47], v[46:47], v[128:129]
	v_pk_mul_f32 v[42:43], v[42:43], v[132:133]
	v_pk_mul_f32 v[38:39], v[38:39], v[136:137]
	v_pk_mul_f32 v[34:35], v[34:35], v[246:247]
	v_pk_mul_f32 v[32:33], v[32:33], v[244:245]
	v_pk_mul_f32 v[28:29], v[28:29], v[126:127]
	v_pk_mul_f32 v[24:25], v[24:25], v[130:131]
	v_pk_mul_f32 v[20:21], v[20:21], v[134:135]
	v_pk_mul_f32 v[30:31], v[30:31], v[128:129]
	v_pk_mul_f32 v[26:27], v[26:27], v[132:133]
	v_pk_mul_f32 v[22:23], v[22:23], v[136:137]
	v_pk_mul_f32 v[18:19], v[18:19], v[246:247]
	v_pk_mul_f32 v[16:17], v[16:17], v[244:245]
	v_pk_mul_f32 v[12:13], v[12:13], v[126:127]
	v_pk_mul_f32 v[8:9], v[8:9], v[130:131]
	v_pk_mul_f32 v[4:5], v[4:5], v[134:135]
	v_pk_mul_f32 v[14:15], v[14:15], v[128:129]
	v_pk_mul_f32 v[10:11], v[10:11], v[132:133]
	v_pk_mul_f32 v[6:7], v[6:7], v[136:137]
	v_pk_mul_f32 v[2:3], v[2:3], v[246:247]
	v_pk_mul_f32 v[0:1], v[0:1], v[244:245]
; __device__ __forceinline__ void partialSM(f32x16& p0, f32x16& p1, float& m_reg, float& mn, float& alpha, const float C, const float thr) {
;     ...
;     const float mnC = -mn * C;
; #pragma unroll
;     for (int r = 0; r < 16; ++r) p0[r] = fmaf(p0[r], C, mnC);
; #pragma unroll
;     for (int r = 0; r < 16; ++r) p1[r] = fmaf(p1[r], C, mnC);
; #pragma unroll
;     for (int r = 0; r < 16; ++r) p0[r] = __builtin_amdgcn_exp2f(p0[r]);
; }
; __device__ __forceinline__ void finishSM(f32x16& p0, f32x16& p1, float alpha, float& l_reg, bf16x8& pa0, bf16x8& pa1, bf16x8& pa2, bf16x8& pa3) {
; #pragma unroll
;     for (int r = 0; r < 16; ++r) p1[r] = __builtin_amdgcn_exp2f(p1[r]);
;     float ps = 0;
; #pragma unroll
;     for (int r = 0; r < 16; ++r) ps += p0[r];
; #pragma unroll
;     for (int r = 0; r < 16; ++r) ps += p1[r];
;     { auto rr = __builtin_amdgcn_permlane32_swap(__float_as_uint(ps), __float_as_uint(ps), false, false);
;       ps = __uint_as_float(rr[0]) + __uint_as_float(rr[1]); }
;     l_reg = l_reg * alpha + ps;
.LBB0_181:
	v_mov_b32_e32 v142, v241
	v_mul_f32_e32 v132, 0xbe38aa3b, v142
	v_mov_b32_e32 v133, v132
	v_fmac_f32_e32 v133, 0x3e38aa3b, v95
	v_exp_f32_e32 v153, v84
	v_exp_f32_e32 v152, v86
	v_exp_f32_e32 v151, v89
	v_exp_f32_e32 v150, v91
	v_exp_f32_e32 v146, v133
	v_pk_fma_f32 v[138:139], v[64:65], s[8:9], v[132:133] op_sel_hi:[1,0,0]
	v_add_f32_e32 v64, v196, v198
	v_fmac_f32_e32 v64, v194, v178
	v_add_f32_e32 v178, v204, v206
	s_add_i32 s52, s52, 2
	v_pk_fma_f32 v[136:137], v[66:67], s[8:9], v[132:133] op_sel_hi:[1,0,0]
	v_pk_fma_f32 v[130:131], v[68:69], s[8:9], v[132:133] op_sel_hi:[1,0,0]
	v_pk_fma_f32 v[128:129], v[70:71], s[8:9], v[132:133] op_sel_hi:[1,0,0]
	v_pk_fma_f32 v[126:127], v[72:73], s[8:9], v[132:133] op_sel_hi:[1,0,0]
	v_pk_fma_f32 v[140:141], v[74:75], s[8:9], v[132:133] op_sel_hi:[1,0,0]
	v_pk_fma_f32 v[134:135], v[76:77], s[8:9], v[132:133] op_sel_hi:[1,0,0]
	v_pk_fma_f32 v[132:133], v[78:79], s[8:9], v[132:133] op_sel_hi:[1,0,0]
	v_fmac_f32_e32 v178, v64, v200
	s_cmp_gt_u32 s37, 32
	s_waitcnt lgkmcnt(0)
	s_barrier
	s_cbranch_scc1 .LBB0_183
	v_mov_b32_e32 v194, v143
	s_branch .LBB0_171
